# v136 + nt on phase-4 Mamba dwordx4 input loads (read-once chunk streams)
# baseline (speedup 1.0000x reference)
; DI void mamba_item(const Ctx& c, int item, char* smem) {
;     ...
;   const int dir = item >> 8, b = (item >> 4) & 15, head = item & 15, gq = head >> 3;
;   const int tid = TIDX;
;   Gla<64> G; G.init(smem, tid);
;   const bf16_t* raw = (const bf16_t*)(p.ws + OFF_R2);
;   const bf16_t* BC = (const bf16_t*)(p.ws + OFF_XN + 32 * MiB);
;   bf16_t* Y = (bf16_t*)p.out + (size_t)dir * NTOK * 1024;
;   const float Aneg = -expf(p.mb_A_log[dir * 16 + head]), dtb = p.mb_dt_bias[dir * 16 + head];
;   const int cvi = tid & 7, tg = tid >> 3, xc = head * 64 + cvi * 8;
;   u32x4 px[4]; bf16_t pdt[2] = {0, 0}; bf16_t pdts = 0;
;     ...
;   MB_PREFETCH(0);
.LBB0_625:
	s_or_b64 exec, exec, s[2:3]
	s_add_i32 s0, s61, 0xffffff00
	s_ashr_i32 s96, s0, 8
	s_load_dwordx16 s[12:27], s[74:75], 0x80
	s_and_b32 s56, s61, 15
	s_lshl_b32 s54, s96, 4
	s_or_b32 s2, s54, s56
	s_ashr_i32 s3, s2, 31
	s_lshl_b64 s[2:3], s[2:3], 2
	s_waitcnt lgkmcnt(0)
	s_add_u32 s52, s22, s2
	s_addc_u32 s53, s23, s3
	s_add_u32 s2, s20, s2
	s_addc_u32 s3, s21, s3
	global_load_dword v23, v0, s[52:53]
	global_load_dword v195, v0, s[2:3]
	s_lshl_b32 s57, s56, 6
	s_cmpk_lt_u32 s0, 0x100
	s_cselect_b64 s[52:53], -1, 0
	s_cmpk_gt_u32 s0, 0xff
	v_cndmask_b32_e64 v24, v148, v147, s[52:53]
	s_waitcnt vmcnt(20)
	v_mov_b32_e32 v8, v0
	v_mov_b32_e32 v9, v0
	v_or_b32_e32 v22, s57, v136
	s_cselect_b64 s[2:3], -1, 0
	s_waitcnt vmcnt(19)
	v_add_u32_e32 v1, -1, v24
	s_lshl_b32 s0, s61, 7
	v_mov_b32_e32 v10, v0
	v_mov_b32_e32 v11, v0
	v_mov_b64_e32 v[4:5], v[8:9]
	s_and_b32 s76, s0, 0x7800
	v_cmp_gt_u32_e32 vcc, s86, v1
	v_lshlrev_b32_e32 v20, 1, v22
	v_mov_b64_e32 v[6:7], v[10:11]
	s_and_saveexec_b64 s[80:81], vcc
	s_cbranch_execz .LBB0_627
	v_or_b32_e32 v1, s76, v1
	s_movk_i32 s0, 0xa20
	v_mul_lo_u32 v2, v1, s0
	v_mov_b32_e32 v3, v0
	v_lshl_add_u64 v[2:3], v[2:3], 1, s[78:79]
	v_mov_b32_e32 v21, v0
	v_lshl_add_u64 v[2:3], v[2:3], 0, v[20:21]
	global_load_dwordx4 v[4:7], v[2:3], off offset:2048 nt
.LBB0_627:
	s_or_b64 exec, exec, s[80:81]
	v_or_b32_e32 v1, s76, v24
	s_movk_i32 s0, 0xa20
	v_cmp_gt_u32_e32 vcc, s86, v24
	v_mul_lo_u32 v16, v1, s0
	s_and_saveexec_b64 s[80:81], vcc
	s_cbranch_execz .LBB0_629
	v_mov_b32_e32 v17, v0
	v_lshl_add_u64 v[2:3], v[16:17], 1, s[78:79]
	v_mov_b32_e32 v21, v0
	v_lshl_add_u64 v[2:3], v[2:3], 0, v[20:21]
	global_load_dwordx4 v[8:11], v[2:3], off offset:2048 nt
.LBB0_629:
	s_or_b64 exec, exec, s[80:81]
	v_mov_b32_e32 v2, v0
	v_mov_b32_e32 v3, v0
	v_mov_b32_e32 v1, v0
	v_mov_b64_e32 v[14:15], v[2:3]
	v_mov_b64_e32 v[12:13], v[0:1]
	s_and_saveexec_b64 s[80:81], vcc
	s_cbranch_execz .LBB0_631
	v_mov_b32_e32 v17, v0
	v_lshl_add_u64 v[12:13], v[16:17], 1, s[78:79]
	v_mov_b32_e32 v21, v0
	v_lshl_add_u64 v[12:13], v[12:13], 0, v[20:21]
	v_add_co_u32_e32 v12, vcc, 0x1000, v12
	s_nop 1
	v_addc_co_u32_e32 v13, vcc, 0, v13, vcc
	global_load_dwordx4 v[12:15], v[12:13], off offset:3136 nt
.LBB0_631:
	s_or_b64 exec, exec, s[80:81]
	v_add_u32_e32 v21, 2, v24
	v_mov_b64_e32 v[18:19], v[2:3]
	v_cmp_gt_u32_e32 vcc, s86, v21
	v_mov_b64_e32 v[16:17], v[0:1]
	s_and_saveexec_b64 s[80:81], vcc
	s_cbranch_execz .LBB0_633
	v_or_b32_e32 v1, s76, v21
	v_mul_lo_u32 v2, v1, s0
	v_mov_b32_e32 v3, v0
	v_lshl_add_u64 v[2:3], v[2:3], 1, s[78:79]
	v_mov_b32_e32 v21, v0
	v_lshl_add_u64 v[2:3], v[2:3], 0, v[20:21]
	global_load_dwordx4 v[16:19], v[2:3], off offset:2048 nt

; DI float bf2f(bf16_t v) { return __uint_as_float(((unsigned)v) << 16); }
; DI float softplusf_(float x) { return x > 20.f ? x : log1pf(expf(x)); }
; #define MB_LOADBC(c_) do { \
;     _Pragma("unroll") for (int i = 0; i < 8; ++i) { const int v_ = tid + i * 256, s_ = v_ >> 5, cv_ = v_ & 31, st_ = (c_) * 64 + s_, t_ = dir ? (SEQ - 1 - st_) : st_; \
;       pbc[i] = ld8(BC + ((size_t)b * SEQ + t_) * 512 + (cv_ < 16 ? 256 + gq * 128 + cv_ * 8 : gq * 128 + (cv_ - 16) * 8)); } } while (0)
; DI void mamba_item(const Ctx& c, int item, char* smem) {
;     ...
;   MB_PREFETCH(0);
;   for (int c = 0; c < SEQ / 64; ++c) {
;     u32x4 pbc[8];
;     MB_LOADBC(c);
;     { asm volatile("" ::: "memory");
;       float cw0[8], cw1[8], cw2[8], cbv[8];
; #pragma unroll
;       for (int j = 0; j < 8; ++j) { cw0[j] = p.mb_conv_w[xc + j]; cw1[j] = p.mb_conv_w[1536 + xc + j]; cw2[j] = p.mb_conv_w[3072 + xc + j]; cbv[j] = p.mb_conv_b[xc + j]; }
;       float R[4][8];
; #pragma unroll
;       for (int j = 0; j < 4; ++j) unpack8(px[j], R[j]);
; #pragma unroll
;       for (int i = 0; i < 2; ++i) {
;         const int pi = dir ? (1 - i) : i;
;         const float dt = softplusf_(bf2f(pdt[dir ? (1 - i) : i]) + dtb);
.LBB0_637:
	v_add_u32_e32 v2, s75, v157
	v_add_u32_e32 v3, s74, v179
	v_add_u32_e32 v52, s75, v158
	v_add_u32_e32 v53, s74, v178
	v_cndmask_b32_e64 v2, v3, v2, s[52:53]
	v_cndmask_b32_e64 v52, v53, v52, s[52:53]
	v_ashrrev_i32_e32 v3, 31, v2
	v_ashrrev_i32_e32 v53, 31, v52
	v_lshl_add_u64 v[2:3], v[2:3], 0, s[76:77]
	v_lshl_add_u64 v[52:53], v[52:53], 0, s[76:77]
	v_lshlrev_b64 v[2:3], 10, v[2:3]
	v_lshlrev_b64 v[52:53], 10, v[52:53]
	v_lshl_add_u64 v[2:3], v[124:125], 0, v[2:3]
	v_lshl_add_u64 v[56:57], v[124:125], 0, v[52:53]
	global_load_dwordx4 v[52:55], v[2:3], off nt
	s_nop 0
	global_load_dwordx4 v[56:59], v[56:57], off nt
	v_add_u32_e32 v2, s75, v159
	v_add_u32_e32 v3, s74, v177
	v_add_u32_e32 v60, s75, v160
	v_add_u32_e32 v61, s74, v176
	v_cndmask_b32_e64 v2, v3, v2, s[52:53]
	v_cndmask_b32_e64 v60, v61, v60, s[52:53]
	v_ashrrev_i32_e32 v3, 31, v2
	v_ashrrev_i32_e32 v61, 31, v60
	v_lshl_add_u64 v[2:3], v[2:3], 0, s[76:77]
	v_lshl_add_u64 v[60:61], v[60:61], 0, s[76:77]
	v_lshlrev_b64 v[2:3], 10, v[2:3]
	v_lshlrev_b64 v[60:61], 10, v[60:61]
	v_lshl_add_u64 v[2:3], v[124:125], 0, v[2:3]
	v_lshl_add_u64 v[64:65], v[124:125], 0, v[60:61]
	global_load_dwordx4 v[60:63], v[2:3], off nt
	s_nop 0
	global_load_dwordx4 v[64:67], v[64:65], off nt
	v_add_u32_e32 v2, s75, v161
	v_add_u32_e32 v3, s74, v175
	v_add_u32_e32 v68, s75, v162
	v_add_u32_e32 v69, s74, v174
	v_cndmask_b32_e64 v2, v3, v2, s[52:53]
	v_cndmask_b32_e64 v68, v69, v68, s[52:53]
	v_ashrrev_i32_e32 v3, 31, v2
	v_ashrrev_i32_e32 v69, 31, v68
	v_lshl_add_u64 v[2:3], v[2:3], 0, s[76:77]
	v_lshl_add_u64 v[68:69], v[68:69], 0, s[76:77]
	v_lshlrev_b64 v[2:3], 10, v[2:3]
	v_lshlrev_b64 v[68:69], 10, v[68:69]
	v_lshl_add_u64 v[2:3], v[124:125], 0, v[2:3]
	v_lshl_add_u64 v[72:73], v[124:125], 0, v[68:69]
	global_load_dwordx4 v[68:71], v[2:3], off nt
	s_nop 0
	global_load_dwordx4 v[72:75], v[72:73], off nt
	v_add_u32_e32 v2, s75, v163
	v_add_u32_e32 v3, s74, v173
	v_add_u32_e32 v76, s75, v164
	v_add_u32_e32 v77, s74, v172
	v_cndmask_b32_e64 v2, v3, v2, s[52:53]
	v_cndmask_b32_e64 v76, v77, v76, s[52:53]
	v_ashrrev_i32_e32 v3, 31, v2
	v_ashrrev_i32_e32 v77, 31, v76
	v_lshl_add_u64 v[2:3], v[2:3], 0, s[76:77]
	v_lshl_add_u64 v[76:77], v[76:77], 0, s[76:77]
	v_lshlrev_b64 v[2:3], 10, v[2:3]
	v_lshlrev_b64 v[76:77], 10, v[76:77]
	v_lshl_add_u64 v[2:3], v[124:125], 0, v[2:3]
	v_lshl_add_u64 v[76:77], v[124:125], 0, v[76:77]
	global_load_dwordx4 v[80:83], v[2:3], off nt
	s_nop 0
	global_load_dwordx4 v[76:79], v[76:77], off nt
	global_load_dwordx4 v[84:87], v[126:127], off offset:16 nt
	global_load_dwordx4 v[100:103], v[126:127], off nt
	global_load_dwordx4 v[88:91], v[128:129], off offset:16 nt
	global_load_dwordx4 v[104:107], v[128:129], off nt
	global_load_dwordx4 v[92:95], v[130:131], off offset:16 nt
	global_load_dwordx4 v[108:111], v[130:131], off nt
	global_load_dwordx4 v[96:99], v[132:133], off offset:16 nt
	global_load_dwordx4 v[112:115], v[132:133], off nt
	s_mov_b64 vcc, s[52:53]
	s_waitcnt vmcnt(16)
	v_cndmask_b32_sdwa v2, v198, v1, vcc dst_sel:WORD_1 dst_unused:UNUSED_PAD src0_sel:DWORD src1_sel:DWORD
	s_nop 0
	v_add_f32_e32 v2, v195, v2
	v_cmp_nlt_f32_e32 vcc, s82, v2
	s_and_saveexec_b64 s[80:81], vcc
	s_cbranch_execz .LBB0_639
; DI float bf2f(bf16_t v) { return __uint_as_float(((unsigned)v) << 16); }
; DI float softplusf_(float x) { return x > 20.f ? x : log1pf(expf(x)); }
; DI void mamba_item(const Ctx& c, int item, char* smem) {
;     ...
;         const float dt = softplusf_(bf2f(pdt[dir ? (1 - i) : i]) + dtb);
	v_mul_f32_e32 v3, 0x3fb8aa3b, v2
	v_rndne_f32_e32 v119, v3
	v_sub_f32_e32 v121, v3, v119
	v_fma_f32 v3, v2, s89, -v3
	v_fmac_f32_e32 v3, 0x32a5705f, v2
	v_add_f32_e32 v3, v121, v3
	v_cvt_i32_f32_e32 v119, v119
	v_exp_f32_e32 v3, v3
	v_cmp_ngt_f32_e32 vcc, s87, v2
	s_mov_b32 s12, 0x3f2aaaab
	v_ldexp_f32 v3, v3, v119
	v_cndmask_b32_e32 v3, 0, v3, vcc
	v_cmp_nlt_f32_e32 vcc, s83, v2
	s_nop 1
	v_cndmask_b32_e32 v119, v192, v3, vcc
	v_add_f32_e32 v121, 1.0, v119
	v_add_f32_e32 v2, -1.0, v121
	v_sub_f32_e32 v3, v2, v121
	v_add_f32_e32 v3, 1.0, v3
	v_sub_f32_e32 v2, v119, v2
	v_add_f32_e32 v199, v2, v3
	v_frexp_mant_f32_e32 v200, v121
	v_cvt_f64_f32_e32 v[2:3], v121
	v_frexp_exp_i32_f64_e32 v2, v[2:3]
	v_cmp_gt_f32_e32 vcc, s12, v200
	s_mov_b32 s12, 0x7f800000
	s_nop 0
	v_subbrev_co_u32_e32 v206, vcc, 0, v2, vcc
	v_sub_u32_e32 v2, 0, v206
	v_ldexp_f32 v3, v121, v2
	v_add_f32_e32 v121, -1.0, v3
	v_add_f32_e32 v200, 1.0, v3
	v_ldexp_f32 v2, v199, v2
	v_add_f32_e32 v199, 1.0, v121
	v_add_f32_e32 v201, -1.0, v200
	v_sub_f32_e32 v199, v3, v199
	v_sub_f32_e32 v3, v3, v201
	v_add_f32_e32 v199, v2, v199
	v_add_f32_e32 v2, v2, v3
	v_add_f32_e32 v207, v200, v2
	v_rcp_f32_e32 v209, v207
	v_sub_f32_e32 v3, v200, v207
	v_add_f32_e32 v208, v2, v3
	v_add_f32_e32 v3, v121, v199
	v_sub_f32_e32 v2, v121, v3
	v_add_f32_e32 v121, v199, v2
	v_mul_f32_e32 v199, v3, v209
	v_mul_f32_e32 v200, v207, v199
	v_fma_f32 v202, v199, v207, -v200
	v_fmac_f32_e32 v202, v199, v208
	v_add_f32_e32 v2, v200, v202
	v_sub_f32_e32 v201, v3, v2
	v_pk_add_f32 v[204:205], v[2:3], v[200:201] neg_lo:[0,1] neg_hi:[0,1]
	v_mov_b32_e32 v203, v2
	v_pk_add_f32 v[2:3], v[204:205], v[202:203] neg_lo:[0,1] neg_hi:[0,1]
	v_cmp_neq_f32_e32 vcc, s12, v119
	v_add_f32_e32 v3, v121, v3
	v_add_f32_e32 v2, v2, v3
	v_add_f32_e32 v3, v201, v2
	v_mul_f32_e32 v121, v209, v3
	v_mul_f32_e32 v200, v207, v121
	v_fma_f32 v202, v121, v207, -v200
	v_fmac_f32_e32 v202, v121, v208
	v_sub_f32_e32 v201, v201, v3
	v_add_f32_e32 v207, v2, v201
	v_add_f32_e32 v2, v200, v202
	v_sub_f32_e32 v201, v3, v2
	v_pk_add_f32 v[204:205], v[2:3], v[200:201] neg_lo:[0,1] neg_hi:[0,1]
	v_mov_b32_e32 v203, v2
	v_pk_add_f32 v[2:3], v[204:205], v[202:203] neg_lo:[0,1] neg_hi:[0,1]
	s_nop 0
	v_add_f32_e32 v3, v207, v3
	v_add_f32_e32 v2, v2, v3
	v_add_f32_e32 v3, v199, v121
	v_add_f32_e32 v2, v201, v2
	v_sub_f32_e32 v199, v3, v199
	v_mul_f32_e32 v2, v209, v2
	v_sub_f32_e32 v121, v121, v199
	v_add_f32_e32 v199, v121, v2
	v_add_f32_e32 v200, v3, v199
	v_mul_f32_e32 v202, v200, v200
	v_fmamk_f32 v2, v202, 0x3e9b6dac, v180
	v_fmaak_f32 v121, v202, v2, 0x3f2aaada
	v_cvt_f32_i32_e32 v2, v206
	v_sub_f32_e32 v3, v200, v3
	v_sub_f32_e32 v3, v199, v3
	v_ldexp_f32 v199, v3, 1
	v_mul_f32_e32 v3, v200, v202
	v_pk_mul_f32 v[202:203], v[2:3], v[120:121]
	v_ldexp_f32 v201, v200, 1
	v_fma_f32 v200, v2, s33, -v202
	v_fmac_f32_e32 v200, 0xb102e308, v2
	v_pk_add_f32 v[2:3], v[202:203], v[200:201]
	v_mov_b32_e32 v204, v202
	v_sub_f32_e32 v121, v3, v201
	v_sub_f32_e32 v121, v203, v121
	v_add_f32_e32 v205, v199, v121
	v_pk_add_f32 v[202:203], v[2:3], v[202:203] neg_lo:[0,1] neg_hi:[0,1]
	v_pk_add_f32 v[206:207], v[2:3], v[204:205]
	v_mov_b32_e32 v201, v2
	v_mov_b32_e32 v203, v207
	v_pk_add_f32 v[208:209], v[200:201], v[202:203] neg_lo:[0,1] neg_hi:[0,1]
	v_pk_add_f32 v[200:201], v[200:201], v[202:203]
	v_mov_b32_e32 v204, v205
	v_pk_add_f32 v[202:203], v[200:201], v[2:3] op_sel:[1,0] op_sel_hi:[0,1] neg_lo:[0,1] neg_hi:[0,1]
	v_pk_add_f32 v[210:211], v[206:207], v[202:203] op_sel_hi:[1,0] neg_lo:[0,1] neg_hi:[0,1]
	v_mov_b32_e32 v206, v207
	v_mov_b32_e32 v207, v201
	v_pk_mov_b32 v[202:203], v[2:3], v[202:203] op_sel:[1,0]
	v_mov_b32_e32 v205, v2
	v_pk_add_f32 v[202:203], v[206:207], v[202:203] neg_lo:[0,1] neg_hi:[0,1]
	v_mov_b32_e32 v210, v208
	v_pk_add_f32 v[2:3], v[204:205], v[202:203] neg_lo:[0,1] neg_hi:[0,1]
	v_mov_b32_e32 v209, v201
	v_pk_add_f32 v[202:203], v[210:211], v[2:3]
	s_nop 0
	v_pk_add_f32 v[204:205], v[202:203], v[202:203] op_sel:[0,1] op_sel_hi:[1,0]
	s_nop 0
	v_pk_add_f32 v[200:201], v[200:201], v[204:205] op_sel:[1,0] op_sel_hi:[0,1]
	v_mov_b32_e32 v203, v200
	v_pk_add_f32 v[206:207], v[202:203], v[208:209] neg_lo:[0,1] neg_hi:[0,1]
	v_mov_b32_e32 v3, v204
	v_sub_f32_e32 v121, v202, v206
	v_pk_add_f32 v[2:3], v[2:3], v[206:207] neg_lo:[0,1] neg_hi:[0,1]
	v_sub_f32_e32 v121, v208, v121
	v_add_f32_e32 v2, v2, v121
	v_add_f32_e32 v2, v2, v3
	v_add_f32_e32 v2, v200, v2
	v_cndmask_b32_e32 v2, v192, v2, vcc
	v_cmp_lt_f32_e64 vcc, |v119|, s72
	s_nop 1
	v_cndmask_b32_e32 v2, v2, v119, vcc

; DI void mamba_item(const Ctx& c, int item, char* smem) {
;     ...
;     if (c + 1 < SEQ / 64) MB_PREFETCH(c + 1);
.LBB0_651:
	v_mov_b32_e32 v2, v0
	v_mov_b32_e32 v3, v0
	v_add_u32_e32 v8, -1, v52
	v_mov_b32_e32 v1, v0
	v_mov_b64_e32 v[6:7], v[2:3]
	v_cmp_gt_u32_e32 vcc, s86, v8
	v_mov_b64_e32 v[4:5], v[0:1]
	s_and_saveexec_b64 s[80:81], vcc
	s_cbranch_execz .LBB0_653
	v_or_b32_e32 v4, s76, v8
	s_movk_i32 s12, 0xa20
	v_mul_lo_u32 v4, v4, s12
	v_mov_b32_e32 v5, v0
	v_lshl_add_u64 v[4:5], v[4:5], 1, v[134:135]
	global_load_dwordx4 v[4:7], v[4:5], off offset:2048 nt
.LBB0_653:
	s_or_b64 exec, exec, s[80:81]
	v_mov_b64_e32 v[10:11], v[2:3]
	v_cmp_gt_u32_e32 vcc, s86, v52
	v_mov_b64_e32 v[8:9], v[0:1]
	s_and_saveexec_b64 s[80:81], vcc
	s_cbranch_execz .LBB0_655
	v_or_b32_e32 v1, s76, v52
	s_movk_i32 s12, 0xa20
	v_mul_lo_u32 v2, v1, s12
	v_mov_b32_e32 v3, v0
	v_lshl_add_u64 v[2:3], v[2:3], 1, v[134:135]
	global_load_dwordx4 v[8:11], v[2:3], off offset:2048 nt
.LBB0_655:
	s_or_b64 exec, exec, s[80:81]
	v_mov_b32_e32 v2, v0
	v_mov_b32_e32 v3, v0
	v_add_u32_e32 v16, 1, v52
	v_mov_b32_e32 v1, v0
	v_mov_b64_e32 v[14:15], v[2:3]
	v_cmp_gt_u32_e32 vcc, s86, v16
	v_mov_b64_e32 v[12:13], v[0:1]
	s_and_saveexec_b64 s[80:81], vcc
	s_cbranch_execz .LBB0_657
	v_or_b32_e32 v12, s76, v16
	s_movk_i32 s12, 0xa20
	v_mul_lo_u32 v12, v12, s12
	v_mov_b32_e32 v13, v0
	v_lshl_add_u64 v[12:13], v[12:13], 1, v[134:135]
	global_load_dwordx4 v[12:15], v[12:13], off offset:2048 nt
.LBB0_657:
	s_or_b64 exec, exec, s[80:81]
	v_add_u32_e32 v53, 2, v52
	v_mov_b64_e32 v[18:19], v[2:3]
	v_cmp_gt_u32_e32 vcc, s86, v53
	v_mov_b64_e32 v[16:17], v[0:1]
	s_and_saveexec_b64 s[80:81], vcc
	s_cbranch_execz .LBB0_659
	v_or_b32_e32 v1, s76, v53
	s_movk_i32 s12, 0xa20
	v_mul_lo_u32 v2, v1, s12
	v_mov_b32_e32 v3, v0
	v_lshl_add_u64 v[2:3], v[2:3], 1, v[134:135]
	global_load_dwordx4 v[16:19], v[2:3], off offset:2048 nt

; DI void mamba_item(const Ctx& c, int item, char* smem) {
;     ...
;   const int dir = item >> 8, b = (item >> 4) & 15, head = item & 15, gq = head >> 3;
;   const int tid = TIDX;
;   Gla<64> G; G.init(smem, tid);
;   const bf16_t* raw = (const bf16_t*)(p.ws + OFF_R2);
;   const bf16_t* BC = (const bf16_t*)(p.ws + OFF_XN + 32 * MiB);
;   bf16_t* Y = (bf16_t*)p.out + (size_t)dir * NTOK * 1024;
;   const float Aneg = -expf(p.mb_A_log[dir * 16 + head]), dtb = p.mb_dt_bias[dir * 16 + head];
;   const int cvi = tid & 7, tg = tid >> 3, xc = head * 64 + cvi * 8;
;   u32x4 px[4]; bf16_t pdt[2] = {0, 0}; bf16_t pdts = 0;
;     ...
;   MB_PREFETCH(0);
.LBB0_715:
	s_or_b64 exec, exec, s[0:1]
	v_readlane_b32 s52, v253, 60
	v_readlane_b32 s53, v253, 61
	s_lshr_b32 s78, s85, 8
	s_load_dwordx16 s[12:27], s[52:53], 0x80
	s_and_b32 s56, s85, 15
	s_lshl_b32 s1, s78, 4
	s_or_b32 s0, s1, s56
	s_lshl_b32 s0, s0, 2
	s_waitcnt vmcnt(17)
	v_mov_b32_e32 v1, s0
	s_waitcnt lgkmcnt(0)
	global_load_dword v23, v1, s[22:23]
	global_load_dword v195, v1, s[20:21]
	s_lshl_b32 s57, s56, 6
	s_cmpk_lt_u32 s85, 0x100
	s_cselect_b64 s[52:53], -1, 0
	s_cmpk_gt_u32 s85, 0xff
	v_cndmask_b32_e64 v24, v148, v147, s[52:53]
	v_mov_b32_e32 v8, v0
	v_mov_b32_e32 v9, v0
	v_or_b32_e32 v22, s57, v136
	s_cselect_b64 s[12:13], -1, 0
	v_add_u32_e32 v1, -1, v24
	s_lshl_b32 s0, s85, 7
	v_mov_b32_e32 v10, v0
	v_mov_b32_e32 v11, v0
	v_mov_b64_e32 v[4:5], v[8:9]
	v_writelane_b32 v252, s12, 24
	s_and_b32 s0, s0, 0x7800
	v_cmp_gt_u32_e32 vcc, s33, v1
	v_lshlrev_b32_e32 v20, 1, v22
	v_mov_b64_e32 v[6:7], v[10:11]
	v_writelane_b32 v252, s13, 25
	s_and_saveexec_b64 s[54:55], vcc
	s_cbranch_execz .LBB0_717
	v_or_b32_e32 v1, s0, v1
	v_mul_lo_u32 v2, v1, s82
	v_mov_b32_e32 v3, v0
	v_lshl_add_u64 v[2:3], v[2:3], 1, s[76:77]
	v_mov_b32_e32 v21, v0
	v_lshl_add_u64 v[2:3], v[2:3], 0, v[20:21]
	global_load_dwordx4 v[4:7], v[2:3], off offset:2048 nt
.LBB0_717:
	s_or_b64 exec, exec, s[54:55]
	v_or_b32_e32 v1, s0, v24
	v_cmp_gt_u32_e32 vcc, s33, v24
	v_mul_lo_u32 v16, v1, s82
	s_and_saveexec_b64 s[54:55], vcc
	s_cbranch_execz .LBB0_719
	v_mov_b32_e32 v17, v0
	v_lshl_add_u64 v[2:3], v[16:17], 1, s[76:77]
	v_mov_b32_e32 v21, v0
	v_lshl_add_u64 v[2:3], v[2:3], 0, v[20:21]
	global_load_dwordx4 v[8:11], v[2:3], off offset:2048 nt
.LBB0_719:
	s_or_b64 exec, exec, s[54:55]
	v_mov_b32_e32 v2, v0
	v_mov_b32_e32 v3, v0
	v_mov_b32_e32 v1, v0
	v_mov_b64_e32 v[14:15], v[2:3]
	v_mov_b64_e32 v[12:13], v[0:1]
	s_and_saveexec_b64 s[54:55], vcc
	s_cbranch_execz .LBB0_721
	v_mov_b32_e32 v17, v0
	v_lshl_add_u64 v[12:13], v[16:17], 1, s[76:77]
	v_mov_b32_e32 v21, v0
	v_lshl_add_u64 v[12:13], v[12:13], 0, v[20:21]
	v_add_co_u32_e32 v12, vcc, 0x1000, v12
	s_nop 1
	v_addc_co_u32_e32 v13, vcc, 0, v13, vcc
	global_load_dwordx4 v[12:15], v[12:13], off offset:3136 nt
.LBB0_721:
	s_or_b64 exec, exec, s[54:55]
	v_add_u32_e32 v21, 2, v24
	v_mov_b64_e32 v[18:19], v[2:3]
	v_cmp_gt_u32_e32 vcc, s33, v21
	v_mov_b64_e32 v[16:17], v[0:1]
	s_and_saveexec_b64 s[54:55], vcc
	s_cbranch_execz .LBB0_723
	v_or_b32_e32 v1, s0, v21
	v_mul_lo_u32 v2, v1, s82
	v_mov_b32_e32 v3, v0
	v_lshl_add_u64 v[2:3], v[2:3], 1, s[76:77]
	v_mov_b32_e32 v21, v0
	v_lshl_add_u64 v[2:3], v[2:3], 0, v[20:21]
	global_load_dwordx4 v[16:19], v[2:3], off offset:2048 nt

; DI float bf2f(bf16_t v) { return __uint_as_float(((unsigned)v) << 16); }
; DI float softplusf_(float x) { return x > 20.f ? x : log1pf(expf(x)); }
; #define MB_LOADBC(c_) do { \
;     _Pragma("unroll") for (int i = 0; i < 8; ++i) { const int v_ = tid + i * 256, s_ = v_ >> 5, cv_ = v_ & 31, st_ = (c_) * 64 + s_, t_ = dir ? (SEQ - 1 - st_) : st_; \
;       pbc[i] = ld8(BC + ((size_t)b * SEQ + t_) * 512 + (cv_ < 16 ? 256 + gq * 128 + cv_ * 8 : gq * 128 + (cv_ - 16) * 8)); } } while (0)
; DI void mamba_item(const Ctx& c, int item, char* smem) {
;     ...
;   MB_PREFETCH(0);
;   for (int c = 0; c < SEQ / 64; ++c) {
;     u32x4 pbc[8];
;     MB_LOADBC(c);
;     { asm volatile("" ::: "memory");
;       float cw0[8], cw1[8], cw2[8], cbv[8];
; #pragma unroll
;       for (int j = 0; j < 8; ++j) { cw0[j] = p.mb_conv_w[xc + j]; cw1[j] = p.mb_conv_w[1536 + xc + j]; cw2[j] = p.mb_conv_w[3072 + xc + j]; cbv[j] = p.mb_conv_b[xc + j]; }
;       float R[4][8];
; #pragma unroll
;       for (int j = 0; j < 4; ++j) unpack8(px[j], R[j]);
; #pragma unroll
;       for (int i = 0; i < 2; ++i) {
;         const int pi = dir ? (1 - i) : i;
;         const float dt = softplusf_(bf2f(pdt[dir ? (1 - i) : i]) + dtb);
.LBB0_727:
	v_add_u32_e32 v2, s86, v157
	v_add_u32_e32 v3, s91, v179
	v_add_u32_e32 v52, s86, v158
	v_add_u32_e32 v53, s91, v178
	v_cndmask_b32_e64 v2, v3, v2, s[52:53]
	v_cndmask_b32_e64 v52, v53, v52, s[52:53]
	v_ashrrev_i32_e32 v3, 31, v2
	v_ashrrev_i32_e32 v53, 31, v52
	v_lshl_add_u64 v[2:3], v[2:3], 0, s[0:1]
	v_lshl_add_u64 v[52:53], v[52:53], 0, s[0:1]
	v_lshlrev_b64 v[2:3], 10, v[2:3]
	v_lshlrev_b64 v[52:53], 10, v[52:53]
	v_lshl_add_u64 v[2:3], v[124:125], 0, v[2:3]
	v_lshl_add_u64 v[56:57], v[124:125], 0, v[52:53]
	global_load_dwordx4 v[52:55], v[2:3], off nt
	s_nop 0
	global_load_dwordx4 v[56:59], v[56:57], off nt
	v_add_u32_e32 v2, s86, v159
	v_add_u32_e32 v3, s91, v177
	v_add_u32_e32 v60, s86, v160
	v_add_u32_e32 v61, s91, v176
	v_cndmask_b32_e64 v2, v3, v2, s[52:53]
	v_cndmask_b32_e64 v60, v61, v60, s[52:53]
	v_ashrrev_i32_e32 v3, 31, v2
	v_ashrrev_i32_e32 v61, 31, v60
	v_lshl_add_u64 v[2:3], v[2:3], 0, s[0:1]
	v_lshl_add_u64 v[60:61], v[60:61], 0, s[0:1]
	v_lshlrev_b64 v[2:3], 10, v[2:3]
	v_lshlrev_b64 v[60:61], 10, v[60:61]
	v_lshl_add_u64 v[2:3], v[124:125], 0, v[2:3]
	v_lshl_add_u64 v[64:65], v[124:125], 0, v[60:61]
	global_load_dwordx4 v[60:63], v[2:3], off nt
	s_nop 0
	global_load_dwordx4 v[64:67], v[64:65], off nt
	v_add_u32_e32 v2, s86, v161
	v_add_u32_e32 v3, s91, v175
	v_add_u32_e32 v68, s86, v162
	v_add_u32_e32 v69, s91, v174
	v_cndmask_b32_e64 v2, v3, v2, s[52:53]
	v_cndmask_b32_e64 v68, v69, v68, s[52:53]
	v_ashrrev_i32_e32 v3, 31, v2
	v_ashrrev_i32_e32 v69, 31, v68
	v_lshl_add_u64 v[2:3], v[2:3], 0, s[0:1]
	v_lshl_add_u64 v[68:69], v[68:69], 0, s[0:1]
	v_lshlrev_b64 v[2:3], 10, v[2:3]
	v_lshlrev_b64 v[68:69], 10, v[68:69]
	v_lshl_add_u64 v[2:3], v[124:125], 0, v[2:3]
	v_lshl_add_u64 v[72:73], v[124:125], 0, v[68:69]
	global_load_dwordx4 v[68:71], v[2:3], off nt
	s_nop 0
	global_load_dwordx4 v[72:75], v[72:73], off nt
	v_add_u32_e32 v2, s86, v163
	v_add_u32_e32 v3, s91, v173
	v_add_u32_e32 v76, s86, v164
	v_add_u32_e32 v77, s91, v172
	v_cndmask_b32_e64 v2, v3, v2, s[52:53]
	v_cndmask_b32_e64 v76, v77, v76, s[52:53]
	v_ashrrev_i32_e32 v3, 31, v2
	v_ashrrev_i32_e32 v77, 31, v76
	v_lshl_add_u64 v[2:3], v[2:3], 0, s[0:1]
	v_lshl_add_u64 v[76:77], v[76:77], 0, s[0:1]
	v_lshlrev_b64 v[2:3], 10, v[2:3]
	v_lshlrev_b64 v[76:77], 10, v[76:77]
	v_lshl_add_u64 v[2:3], v[124:125], 0, v[2:3]
	v_lshl_add_u64 v[76:77], v[124:125], 0, v[76:77]
	global_load_dwordx4 v[80:83], v[2:3], off nt
	s_nop 0
	global_load_dwordx4 v[76:79], v[76:77], off nt
	global_load_dwordx4 v[84:87], v[126:127], off offset:16 nt
	global_load_dwordx4 v[100:103], v[126:127], off nt
	global_load_dwordx4 v[88:91], v[128:129], off offset:16 nt
	global_load_dwordx4 v[104:107], v[128:129], off nt
	global_load_dwordx4 v[92:95], v[130:131], off offset:16 nt
	global_load_dwordx4 v[108:111], v[130:131], off nt
	global_load_dwordx4 v[96:99], v[132:133], off offset:16 nt
	global_load_dwordx4 v[112:115], v[132:133], off nt
	s_mov_b64 vcc, s[52:53]
	s_waitcnt vmcnt(16)
	v_cndmask_b32_sdwa v2, v198, v1, vcc dst_sel:WORD_1 dst_unused:UNUSED_PAD src0_sel:DWORD src1_sel:DWORD
	s_nop 0
	v_add_f32_e32 v2, v195, v2
	v_cmp_nlt_f32_e32 vcc, s75, v2
	s_and_saveexec_b64 s[78:79], vcc
	s_cbranch_execz .LBB0_729
; DI float bf2f(bf16_t v) { return __uint_as_float(((unsigned)v) << 16); }
; DI float softplusf_(float x) { return x > 20.f ? x : log1pf(expf(x)); }
; DI void mamba_item(const Ctx& c, int item, char* smem) {
;     ...
;         const float dt = softplusf_(bf2f(pdt[dir ? (1 - i) : i]) + dtb);
	v_mul_f32_e32 v3, 0x3fb8aa3b, v2
	v_rndne_f32_e32 v119, v3
	v_sub_f32_e32 v121, v3, v119
	v_fma_f32 v3, v2, s84, -v3
	v_fmac_f32_e32 v3, 0x32a5705f, v2
	v_add_f32_e32 v3, v121, v3
	v_cvt_i32_f32_e32 v119, v119
	v_exp_f32_e32 v3, v3
	v_cmp_ngt_f32_e32 vcc, s72, v2
	v_ldexp_f32 v3, v3, v119
	s_nop 0
	v_cndmask_b32_e32 v3, 0, v3, vcc
	v_cmp_nlt_f32_e32 vcc, s73, v2
	s_nop 1
	v_cndmask_b32_e32 v119, v192, v3, vcc
	v_add_f32_e32 v121, 1.0, v119
	v_add_f32_e32 v2, -1.0, v121
	v_sub_f32_e32 v3, v2, v121
	v_add_f32_e32 v3, 1.0, v3
	v_sub_f32_e32 v2, v119, v2
	v_add_f32_e32 v199, v2, v3
	v_frexp_mant_f32_e32 v200, v121
	v_cvt_f64_f32_e32 v[2:3], v121
	v_frexp_exp_i32_f64_e32 v2, v[2:3]
	v_cmp_gt_f32_e32 vcc, s87, v200
	s_nop 1
	v_subbrev_co_u32_e32 v206, vcc, 0, v2, vcc
	v_sub_u32_e32 v2, 0, v206
	v_ldexp_f32 v3, v121, v2
	v_add_f32_e32 v121, -1.0, v3
	v_add_f32_e32 v200, 1.0, v3
	v_ldexp_f32 v2, v199, v2
	v_add_f32_e32 v199, 1.0, v121
	v_add_f32_e32 v201, -1.0, v200
	v_sub_f32_e32 v199, v3, v199
	v_sub_f32_e32 v3, v3, v201
	v_add_f32_e32 v199, v2, v199
	v_add_f32_e32 v2, v2, v3
	v_add_f32_e32 v207, v200, v2
	v_rcp_f32_e32 v209, v207
	v_sub_f32_e32 v3, v200, v207
	v_add_f32_e32 v208, v2, v3
	v_add_f32_e32 v3, v121, v199
	v_sub_f32_e32 v2, v121, v3
	v_add_f32_e32 v121, v199, v2
	v_mul_f32_e32 v199, v3, v209
	v_mul_f32_e32 v200, v207, v199
	v_fma_f32 v202, v199, v207, -v200
	v_fmac_f32_e32 v202, v199, v208
	v_add_f32_e32 v2, v200, v202
	v_sub_f32_e32 v201, v3, v2
	v_pk_add_f32 v[204:205], v[2:3], v[200:201] neg_lo:[0,1] neg_hi:[0,1]
	v_mov_b32_e32 v203, v2
	v_pk_add_f32 v[2:3], v[204:205], v[202:203] neg_lo:[0,1] neg_hi:[0,1]
	v_cmp_neq_f32_e32 vcc, s74, v119
	v_add_f32_e32 v3, v121, v3
	v_add_f32_e32 v2, v2, v3
	v_add_f32_e32 v3, v201, v2
	v_mul_f32_e32 v121, v209, v3
	v_mul_f32_e32 v200, v207, v121
	v_fma_f32 v202, v121, v207, -v200
	v_fmac_f32_e32 v202, v121, v208
	v_sub_f32_e32 v201, v201, v3
	v_add_f32_e32 v207, v2, v201
	v_add_f32_e32 v2, v200, v202
	v_sub_f32_e32 v201, v3, v2
	v_pk_add_f32 v[204:205], v[2:3], v[200:201] neg_lo:[0,1] neg_hi:[0,1]
	v_mov_b32_e32 v203, v2
	v_pk_add_f32 v[2:3], v[204:205], v[202:203] neg_lo:[0,1] neg_hi:[0,1]
	s_nop 0
	v_add_f32_e32 v3, v207, v3
	v_add_f32_e32 v2, v2, v3
	v_add_f32_e32 v3, v199, v121
	v_add_f32_e32 v2, v201, v2
	v_sub_f32_e32 v199, v3, v199
	v_mul_f32_e32 v2, v209, v2
	v_sub_f32_e32 v121, v121, v199
	v_add_f32_e32 v199, v121, v2
	v_add_f32_e32 v200, v3, v199
	v_mul_f32_e32 v202, v200, v200
	v_fmamk_f32 v2, v202, 0x3e9b6dac, v180
	v_fmaak_f32 v121, v202, v2, 0x3f2aaada
	v_cvt_f32_i32_e32 v2, v206
	v_sub_f32_e32 v3, v200, v3
	v_sub_f32_e32 v3, v199, v3
	v_ldexp_f32 v199, v3, 1
	v_mul_f32_e32 v3, v200, v202
	v_pk_mul_f32 v[202:203], v[2:3], v[120:121]
	v_ldexp_f32 v201, v200, 1
	v_fma_f32 v200, v2, s88, -v202
	v_fmac_f32_e32 v200, 0xb102e308, v2
	v_pk_add_f32 v[2:3], v[202:203], v[200:201]
	v_mov_b32_e32 v204, v202
	v_sub_f32_e32 v121, v3, v201
	v_sub_f32_e32 v121, v203, v121
	v_add_f32_e32 v205, v199, v121
	v_pk_add_f32 v[202:203], v[2:3], v[202:203] neg_lo:[0,1] neg_hi:[0,1]
	v_pk_add_f32 v[206:207], v[2:3], v[204:205]
	v_mov_b32_e32 v201, v2
	v_mov_b32_e32 v203, v207
	v_pk_add_f32 v[208:209], v[200:201], v[202:203] neg_lo:[0,1] neg_hi:[0,1]
	v_pk_add_f32 v[200:201], v[200:201], v[202:203]
	v_mov_b32_e32 v204, v205
	v_pk_add_f32 v[202:203], v[200:201], v[2:3] op_sel:[1,0] op_sel_hi:[0,1] neg_lo:[0,1] neg_hi:[0,1]
	v_pk_add_f32 v[210:211], v[206:207], v[202:203] op_sel_hi:[1,0] neg_lo:[0,1] neg_hi:[0,1]
	v_mov_b32_e32 v206, v207
	v_mov_b32_e32 v207, v201
	v_pk_mov_b32 v[202:203], v[2:3], v[202:203] op_sel:[1,0]
	v_mov_b32_e32 v205, v2
	v_pk_add_f32 v[202:203], v[206:207], v[202:203] neg_lo:[0,1] neg_hi:[0,1]
	v_mov_b32_e32 v210, v208
	v_pk_add_f32 v[2:3], v[204:205], v[202:203] neg_lo:[0,1] neg_hi:[0,1]
	v_mov_b32_e32 v209, v201
	v_pk_add_f32 v[202:203], v[210:211], v[2:3]
	s_nop 0
	v_pk_add_f32 v[204:205], v[202:203], v[202:203] op_sel:[0,1] op_sel_hi:[1,0]
	s_nop 0
	v_pk_add_f32 v[200:201], v[200:201], v[204:205] op_sel:[1,0] op_sel_hi:[0,1]
	v_mov_b32_e32 v203, v200
	v_pk_add_f32 v[206:207], v[202:203], v[208:209] neg_lo:[0,1] neg_hi:[0,1]
	v_mov_b32_e32 v3, v204
	v_sub_f32_e32 v121, v202, v206
	v_pk_add_f32 v[2:3], v[2:3], v[206:207] neg_lo:[0,1] neg_hi:[0,1]
	v_sub_f32_e32 v121, v208, v121
	v_add_f32_e32 v2, v2, v121
	v_add_f32_e32 v2, v2, v3
	v_add_f32_e32 v2, v200, v2
	v_cndmask_b32_e32 v2, v192, v2, vcc
	v_cmp_lt_f32_e64 vcc, |v119|, s89
	s_nop 1
	v_cndmask_b32_e32 v2, v2, v119, vcc

; DI void mamba_item(const Ctx& c, int item, char* smem) {
;     ...
;     if (c + 1 < SEQ / 64) MB_PREFETCH(c + 1);
.LBB0_741:
	v_mov_b32_e32 v2, v0
	v_mov_b32_e32 v3, v0
	v_add_u32_e32 v8, -1, v52
	v_mov_b32_e32 v1, v0
	v_mov_b64_e32 v[6:7], v[2:3]
	v_cmp_gt_u32_e32 vcc, s33, v8
	v_mov_b64_e32 v[4:5], v[0:1]
	s_and_saveexec_b64 s[78:79], vcc
	s_cbranch_execz .LBB0_743
	v_or_b32_e32 v4, s0, v8
	v_mul_lo_u32 v4, v4, s82
	v_mov_b32_e32 v5, v0
	v_lshl_add_u64 v[4:5], v[4:5], 1, v[134:135]
	global_load_dwordx4 v[4:7], v[4:5], off offset:2048 nt
.LBB0_743:
	s_or_b64 exec, exec, s[78:79]
	v_mov_b64_e32 v[10:11], v[2:3]
	v_cmp_gt_u32_e32 vcc, s33, v52
	v_mov_b64_e32 v[8:9], v[0:1]
	s_and_saveexec_b64 s[78:79], vcc
	s_cbranch_execz .LBB0_745
	v_or_b32_e32 v1, s0, v52
	v_mul_lo_u32 v2, v1, s82
	v_mov_b32_e32 v3, v0
	v_lshl_add_u64 v[2:3], v[2:3], 1, v[134:135]
	global_load_dwordx4 v[8:11], v[2:3], off offset:2048 nt
.LBB0_745:
	s_or_b64 exec, exec, s[78:79]
	v_mov_b32_e32 v2, v0
	v_mov_b32_e32 v3, v0
	v_add_u32_e32 v16, 1, v52
	v_mov_b32_e32 v1, v0
	v_mov_b64_e32 v[14:15], v[2:3]
	v_cmp_gt_u32_e32 vcc, s33, v16
	v_mov_b64_e32 v[12:13], v[0:1]
	s_and_saveexec_b64 s[78:79], vcc
	s_cbranch_execz .LBB0_747
	v_or_b32_e32 v12, s0, v16
	v_mul_lo_u32 v12, v12, s82
	v_mov_b32_e32 v13, v0
	v_lshl_add_u64 v[12:13], v[12:13], 1, v[134:135]
	global_load_dwordx4 v[12:15], v[12:13], off offset:2048 nt
.LBB0_747:
	s_or_b64 exec, exec, s[78:79]
	v_add_u32_e32 v53, 2, v52
	v_mov_b64_e32 v[18:19], v[2:3]
	v_cmp_gt_u32_e32 vcc, s33, v53
	v_mov_b64_e32 v[16:17], v[0:1]
	s_and_saveexec_b64 s[78:79], vcc
	s_cbranch_execz .LBB0_749
	v_or_b32_e32 v1, s0, v53
	v_mul_lo_u32 v2, v1, s82
	v_mov_b32_e32 v3, v0
	v_lshl_add_u64 v[2:3], v[2:3], 1, v[134:135]
	global_load_dwordx4 v[16:19], v[2:3], off offset:2048 nt
